# attention steady loop: row sums as 15 v_pk_add_f32 (f32 reassociation) and bias-read addresses as one base + ds offsets
# baseline (speedup 1.0000x reference)
.LBB0_47:
	v_add_u32_e32 v0, s20, v224
	ds_read_b64_tr_b16 v[2:3], v0 offset:24576
	ds_read_b64_tr_b16 v[4:5], v0 offset:25088
	v_pk_add_f32 v[248:249], v[96:97], v[98:99]
	v_pk_add_f32 v[248:249], v[100:101], v[248:249]
	s_waitcnt lgkmcnt(9)
	v_mfma_f32_32x32x16_bf16 v[64:79], v[172:175], v[112:115], v[64:79]
	v_cvt_pk_bf16_f32 v140, v96, v97
	v_cvt_pk_bf16_f32 v141, v98, v99
	ds_read_b64_tr_b16 v[6:7], v0 offset:28672
	ds_read_b64_tr_b16 v[8:9], v0 offset:29184
	v_pk_add_f32 v[248:249], v[102:103], v[248:249]
	v_pk_add_f32 v[248:249], v[104:105], v[248:249]
	s_waitcnt lgkmcnt(10)
	v_mfma_f32_32x32x16_bf16 v[48:63], v[168:171], v[112:115], v[48:63]
	v_cvt_pk_bf16_f32 v142, v100, v101
	v_cvt_pk_bf16_f32 v143, v102, v103
	ds_read_b64_tr_b16 v[10:11], v0 offset:25600
	ds_read_b64_tr_b16 v[12:13], v0 offset:26112
	v_pk_add_f32 v[248:249], v[106:107], v[248:249]
	v_pk_add_f32 v[248:249], v[108:109], v[248:249]
	s_waitcnt lgkmcnt(11)
	v_mfma_f32_32x32x16_bf16 v[64:79], v[164:167], v[116:119], v[64:79]
	v_cvt_pk_bf16_f32 v136, v104, v105
	v_cvt_pk_bf16_f32 v137, v106, v107
	ds_read_b64_tr_b16 v[164:165], v0 offset:29696
	ds_read_b64_tr_b16 v[166:167], v0 offset:30208
	v_pk_add_f32 v[248:249], v[110:111], v[248:249]
	v_pk_add_f32 v[248:249], v[80:81], v[248:249]
	s_waitcnt lgkmcnt(12)
	v_mfma_f32_32x32x16_bf16 v[48:63], v[160:163], v[116:119], v[48:63]
	v_cvt_pk_bf16_f32 v138, v108, v109
	v_cvt_pk_bf16_f32 v139, v110, v111
	ds_read_b64_tr_b16 v[168:169], v0 offset:26624
	ds_read_b64_tr_b16 v[170:171], v0 offset:27136
	v_pk_add_f32 v[248:249], v[82:83], v[248:249]
	v_pk_add_f32 v[248:249], v[84:85], v[248:249]
	s_waitcnt lgkmcnt(13)
	v_mfma_f32_32x32x16_bf16 v[64:79], v[156:159], v[120:123], v[64:79]
	v_cvt_pk_bf16_f32 v132, v80, v81
	v_cvt_pk_bf16_f32 v133, v82, v83
	ds_read_b64_tr_b16 v[172:173], v0 offset:30720
	ds_read_b64_tr_b16 v[174:175], v0 offset:31232
	v_pk_add_f32 v[248:249], v[86:87], v[248:249]
	v_pk_add_f32 v[248:249], v[88:89], v[248:249]
	s_waitcnt lgkmcnt(14)
	v_mfma_f32_32x32x16_bf16 v[48:63], v[152:155], v[120:123], v[48:63]
	v_cvt_pk_bf16_f32 v134, v84, v85
	v_cvt_pk_bf16_f32 v135, v86, v87
	ds_read_b64_tr_b16 v[152:153], v0 offset:27648
	ds_read_b64_tr_b16 v[154:155], v0 offset:28160
	v_pk_add_f32 v[248:249], v[90:91], v[248:249]
	v_pk_add_f32 v[248:249], v[92:93], v[248:249]
	s_waitcnt lgkmcnt(14)
	v_mfma_f32_32x32x16_bf16 v[64:79], v[148:151], v[124:127], v[64:79]
	v_cvt_pk_bf16_f32 v128, v88, v89
	v_cvt_pk_bf16_f32 v129, v90, v91
	ds_read_b64_tr_b16 v[184:185], v0 offset:31744
	ds_read_b64_tr_b16 v[186:187], v0 offset:32256
	v_pk_add_f32 v[248:249], v[94:95], v[248:249]
	v_mfma_f32_32x32x16_bf16 v[48:63], v[144:147], v[124:127], v[48:63]
	v_add_f32_e32 v14, v248, v249
	v_cvt_pk_bf16_f32 v130, v92, v93
	v_cvt_pk_bf16_f32 v131, v94, v95
	v_add_u32_e32 v0, 0, v227
	v_add_u32_e32 v15, 0x15200, v0
	ds_read_b128 v[96:99], v15
	ds_read_b128 v[80:83], v15 offset:128
	ds_read_b128 v[100:103], v15 offset:32
	ds_read_b128 v[84:87], v15 offset:160
	ds_read_b128 v[104:107], v15 offset:64
	ds_read_b128 v[88:91], v15 offset:192
	ds_read_b128 v[108:111], v15 offset:96
	s_add_i32 s18, s7, s99
	ds_read_b128 v[92:95], v15 offset:224
	v_lshl_add_u64 v[144:145], v[194:195], 0, s[24:25]
	s_mov_b32 s20, m0
	s_mov_b32 m0, s18
	s_nop 0
	global_load_lds_dwordx4 v[144:145], off
	s_mov_b32 m0, s20
	s_add_i32 s18, s29, s6
	v_lshl_add_u64 v[144:145], v[214:215], 0, s[24:25]
	s_mov_b32 s20, m0
	s_mov_b32 m0, s18
	s_nop 0
	global_load_lds_dwordx4 v[144:145], off
	s_mov_b32 m0, s20
	s_lshl_b32 s18, 1, s44
	s_and_b32 s18, s18, s81
	s_cmp_lg_u32 s18, 0
	v_add_f32_e32 v14, v225, v14
	s_cselect_b64 s[20:21], -1, 0
	s_cmp_eq_u32 s18, 0
	s_cbranch_scc1 .LBB0_49
	s_add_i32 s18, s33, 0
	s_add_i32 s18, s18, 0x17104
	v_mov_b32_e32 v15, s18
	ds_read_b32 v212, v15
	s_waitcnt lgkmcnt(0)
	v_mul_f32_e32 v14, v14, v212

.LBB0_51:
	s_add_i32 s20, s29, 0x2000
	v_add_u32_e32 v15, s7, v224
	ds_read_b64_tr_b16 v[6:7], v15 offset:24576
	ds_read_b64_tr_b16 v[8:9], v15 offset:25088
	v_pk_add_f32 v[248:249], v[64:65], v[66:67]
	v_pk_add_f32 v[248:249], v[68:69], v[248:249]
	s_waitcnt lgkmcnt(9)
	v_mfma_f32_32x32x16_bf16 v[96:111], v[144:147], v[112:115], v[96:111]
	v_cvt_pk_bf16_f32 v140, v64, v65
	v_cvt_pk_bf16_f32 v141, v66, v67
	ds_read_b64_tr_b16 v[144:145], v15 offset:28672
	ds_read_b64_tr_b16 v[146:147], v15 offset:29184
	v_pk_add_f32 v[248:249], v[70:71], v[248:249]
	v_pk_add_f32 v[248:249], v[72:73], v[248:249]
	s_waitcnt lgkmcnt(10)
	v_mfma_f32_32x32x16_bf16 v[80:95], v[180:183], v[112:115], v[80:95]
	v_cvt_pk_bf16_f32 v142, v68, v69
	v_cvt_pk_bf16_f32 v143, v70, v71
	ds_read_b64_tr_b16 v[152:153], v15 offset:25600
	ds_read_b64_tr_b16 v[154:155], v15 offset:26112
	v_pk_add_f32 v[248:249], v[74:75], v[248:249]
	v_pk_add_f32 v[248:249], v[76:77], v[248:249]
	s_waitcnt lgkmcnt(11)
	v_mfma_f32_32x32x16_bf16 v[96:111], v[176:179], v[116:119], v[96:111]
	v_cvt_pk_bf16_f32 v136, v72, v73
	v_cvt_pk_bf16_f32 v137, v74, v75
	ds_read_b64_tr_b16 v[176:177], v15 offset:29696
	ds_read_b64_tr_b16 v[178:179], v15 offset:30208
	v_pk_add_f32 v[248:249], v[78:79], v[248:249]
	v_pk_add_f32 v[248:249], v[48:49], v[248:249]
	s_waitcnt lgkmcnt(12)
	v_mfma_f32_32x32x16_bf16 v[80:95], v[160:163], v[116:119], v[80:95]
	v_cvt_pk_bf16_f32 v138, v76, v77
	v_cvt_pk_bf16_f32 v139, v78, v79
	ds_read_b64_tr_b16 v[180:181], v15 offset:26624
	ds_read_b64_tr_b16 v[182:183], v15 offset:27136
	v_pk_add_f32 v[248:249], v[50:51], v[248:249]
	v_pk_add_f32 v[248:249], v[52:53], v[248:249]
	s_waitcnt lgkmcnt(13)
	v_mfma_f32_32x32x16_bf16 v[96:111], v[156:159], v[120:123], v[96:111]
	v_cvt_pk_bf16_f32 v132, v48, v49
	v_cvt_pk_bf16_f32 v133, v50, v51
	ds_read_b64_tr_b16 v[184:185], v15 offset:30720
	ds_read_b64_tr_b16 v[186:187], v15 offset:31232
	v_pk_add_f32 v[248:249], v[54:55], v[248:249]
	v_pk_add_f32 v[248:249], v[56:57], v[248:249]
	s_waitcnt lgkmcnt(14)
	v_mfma_f32_32x32x16_bf16 v[80:95], v[148:151], v[120:123], v[80:95]
	v_cvt_pk_bf16_f32 v134, v52, v53
	v_cvt_pk_bf16_f32 v135, v54, v55
	ds_read_b64_tr_b16 v[188:189], v15 offset:27648
	ds_read_b64_tr_b16 v[190:191], v15 offset:28160
	s_waitcnt lgkmcnt(14)
	v_mfma_f32_32x32x16_bf16 v[96:111], v[10:13], v[124:127], v[96:111]
	v_pk_add_f32 v[248:249], v[58:59], v[248:249]
	v_pk_add_f32 v[248:249], v[60:61], v[248:249]
	v_cvt_pk_bf16_f32 v128, v56, v57
	v_cvt_pk_bf16_f32 v129, v58, v59
	ds_read_b64_tr_b16 v[10:11], v15 offset:31744
	ds_read_b64_tr_b16 v[12:13], v15 offset:32256
	v_mfma_f32_32x32x16_bf16 v[80:95], v[2:5], v[124:127], v[80:95]
	v_pk_add_f32 v[248:249], v[62:63], v[248:249]
	v_add_f32_e32 v2, v248, v249
	v_cvt_pk_bf16_f32 v130, v60, v61
	v_cvt_pk_bf16_f32 v131, v62, v63
	v_add_u32_e32 v3, 0x15300, v0
	ds_read_b128 v[64:67], v3
	ds_read_b128 v[48:51], v3 offset:128
	ds_read_b128 v[68:71], v3 offset:32
	ds_read_b128 v[52:55], v3 offset:160
	ds_read_b128 v[72:75], v3 offset:64
	s_cmpk_lg_i32 s29, 0x4000
	ds_read_b128 v[56:59], v3 offset:192
	s_cselect_b32 s7, s20, 0
	s_add_i32 s18, s29, s99
	ds_read_b128 v[76:79], v3 offset:96
	ds_read_b128 v[60:63], v3 offset:224
	s_mov_b32 s20, m0
	s_mov_b32 m0, s18
	s_nop 0
	global_load_lds_dwordx4 v[194:195], off
	s_mov_b32 m0, s20
	s_add_i32 s18, s7, s6
	s_mov_b32 s20, m0
	s_mov_b32 m0, s18
	s_nop 0
	global_load_lds_dwordx4 v[214:215], off
	s_mov_b32 m0, s20
	s_lshl_b32 s18, 2, s44
	s_and_b32 s18, s18, s81
	s_cmp_lg_u32 s18, 0
	v_add_f32_e32 v225, v14, v2
	s_cselect_b64 s[20:21], -1, 0
	s_cmp_eq_u32 s18, 0
	s_cbranch_scc1 .LBB0_53
	s_add_i32 s18, s33, 0
	s_add_i32 s18, s18, 0x17108
	v_mov_b32_e32 v0, s18
	ds_read_b32 v212, v0
	s_waitcnt lgkmcnt(0)
	v_mul_f32_e32 v225, v225, v212
